# phase 0 xb/rstd1 row loop: the eight row loads issued together with counted waits instead of load->vmcnt(0)->store per chunk (same arithmetic order)
# speedup vs baseline: 1.0107x; 1.0044x over previous
.LBB0_55:
	s_waitcnt lgkmcnt(0)
	global_load_dwordx4 v[16:19], v[8:9], off offset:-4096
	global_load_dwordx4 v[20:23], v[8:9], off offset:-3072
	global_load_dwordx4 v[24:27], v[8:9], off offset:-2048
	global_load_dwordx4 v[28:31], v[8:9], off offset:-1024
	global_load_dwordx4 v[32:35], v[8:9], off
	global_load_dwordx4 v[36:39], v[8:9], off offset:1024
	global_load_dwordx4 v[40:43], v[8:9], off offset:2048
	global_load_dwordx4 v[44:47], v[8:9], off offset:3072
	v_lshl_add_u64 v[50:51], s[70:71], 0, v[6:7]
	v_add_co_u32_e32 v48, vcc, s3, v50
	s_nop 1
	v_addc_co_u32_e32 v49, vcc, 0, v51, vcc
	s_waitcnt vmcnt(7)
	v_cvt_pk_bf16_f32 v52, v16, v17
	v_cvt_pk_bf16_f32 v53, v18, v19
	global_store_dwordx2 v[48:49], v[52:53], off
	v_pk_mul_f32 v[16:17], v[16:17], v[16:17]
	v_pk_mul_f32 v[18:19], v[18:19], v[18:19]
	v_add_f32_e32 v15, v16, v17
	v_add_f32_e32 v15, v15, v18
	v_add_f32_e32 v15, v15, v19
	s_waitcnt vmcnt(7)
	v_cvt_pk_bf16_f32 v54, v20, v21
	v_cvt_pk_bf16_f32 v55, v22, v23
	global_store_dwordx2 v[48:49], v[54:55], off offset:512
	v_pk_mul_f32 v[16:17], v[20:21], v[20:21]
	v_pk_mul_f32 v[18:19], v[22:23], v[22:23]
	v_add_f32_e32 v16, v16, v17
	v_add_f32_e32 v16, v16, v18
	v_add_f32_e32 v16, v16, v19
	v_add_f32_e32 v15, v15, v16
	s_waitcnt vmcnt(7)
	v_cvt_pk_bf16_f32 v56, v24, v25
	v_cvt_pk_bf16_f32 v57, v26, v27
	global_store_dwordx2 v[48:49], v[56:57], off offset:1024
	v_pk_mul_f32 v[16:17], v[24:25], v[24:25]
	v_pk_mul_f32 v[18:19], v[26:27], v[26:27]
	v_add_f32_e32 v16, v16, v17
	v_add_f32_e32 v16, v16, v18
	v_add_f32_e32 v16, v16, v19
	v_add_f32_e32 v15, v15, v16
	s_waitcnt vmcnt(7)
	v_cvt_pk_bf16_f32 v58, v28, v29
	v_cvt_pk_bf16_f32 v59, v30, v31
	global_store_dwordx2 v[48:49], v[58:59], off offset:1536
	v_pk_mul_f32 v[16:17], v[28:29], v[28:29]
	v_pk_mul_f32 v[18:19], v[30:31], v[30:31]
	v_add_f32_e32 v16, v16, v17
	v_add_f32_e32 v16, v16, v18
	v_add_f32_e32 v16, v16, v19
	v_add_f32_e32 v15, v15, v16
	s_waitcnt vmcnt(7)
	v_cvt_pk_bf16_f32 v60, v32, v33
	v_cvt_pk_bf16_f32 v61, v34, v35
	global_store_dwordx2 v[48:49], v[60:61], off offset:2048
	v_pk_mul_f32 v[16:17], v[32:33], v[32:33]
	v_pk_mul_f32 v[18:19], v[34:35], v[34:35]
	v_add_f32_e32 v16, v16, v17
	v_add_f32_e32 v16, v16, v18
	v_add_f32_e32 v16, v16, v19
	v_add_f32_e32 v15, v15, v16
	s_waitcnt vmcnt(7)
	v_cvt_pk_bf16_f32 v62, v36, v37
	v_cvt_pk_bf16_f32 v63, v38, v39
	global_store_dwordx2 v[48:49], v[62:63], off offset:2560
	v_pk_mul_f32 v[16:17], v[36:37], v[36:37]
	v_pk_mul_f32 v[18:19], v[38:39], v[38:39]
	v_add_f32_e32 v16, v16, v17
	v_add_f32_e32 v16, v16, v18
	v_add_f32_e32 v16, v16, v19
	v_add_f32_e32 v15, v15, v16
	s_waitcnt vmcnt(7)
	v_cvt_pk_bf16_f32 v64, v40, v41
	v_cvt_pk_bf16_f32 v65, v42, v43
	global_store_dwordx2 v[48:49], v[64:65], off offset:3072
	v_pk_mul_f32 v[16:17], v[40:41], v[40:41]
	v_pk_mul_f32 v[18:19], v[42:43], v[42:43]
	v_add_f32_e32 v16, v16, v17
	v_add_f32_e32 v16, v16, v18
	v_add_f32_e32 v68, v16, v19
	v_add_f32_e32 v15, v15, v68
	s_waitcnt vmcnt(7)
	v_cvt_pk_bf16_f32 v66, v44, v45
	v_cvt_pk_bf16_f32 v67, v46, v47
	global_store_dwordx2 v[48:49], v[66:67], off offset:3584
	v_pk_mul_f32 v[16:17], v[44:45], v[44:45]
	v_pk_mul_f32 v[18:19], v[46:47], v[46:47]
	v_add_f32_e32 v16, v16, v17
	v_add_f32_e32 v16, v16, v18
	v_add_f32_e32 v16, v16, v19
	v_add_f32_e32 v15, v15, v16
	ds_bpermute_b32 v16, v1, v15
	s_waitcnt lgkmcnt(0)
	v_add_f32_e32 v15, v15, v16
	ds_bpermute_b32 v16, v10, v15
	s_waitcnt lgkmcnt(0)
	v_add_f32_e32 v15, v15, v16
	ds_bpermute_b32 v16, v11, v15
	s_waitcnt lgkmcnt(0)
	v_add_f32_e32 v15, v15, v16
	ds_bpermute_b32 v16, v12, v15
	s_waitcnt lgkmcnt(0)
	v_add_f32_e32 v15, v15, v16
	ds_bpermute_b32 v16, v13, v15
	s_waitcnt lgkmcnt(0)
	v_add_f32_e32 v15, v15, v16
	ds_bpermute_b32 v16, v14, v15
	s_and_saveexec_b64 s[22:23], s[6:7]
	s_cbranch_execz .LBB0_54
	s_waitcnt lgkmcnt(0)
	v_add_f32_e32 v15, v15, v16
	v_fmamk_f32 v15, v15, 0x3a000000, v3
	v_mul_f32_e32 v16, 0x4b800000, v15
	v_cmp_gt_f32_e32 vcc, s13, v15
	s_nop 1
	v_cndmask_b32_e32 v15, v15, v16, vcc
	v_rsq_f32_e32 v15, v15
	s_nop 0
	v_mul_f32_e32 v16, 0x45800000, v15
	v_cndmask_b32_e32 v15, v15, v16, vcc
	v_lshl_add_u64 v[16:17], s[70:71], 0, v[4:5]
	global_store_dword v[16:17], v15, off
	s_branch .LBB0_54

.Lat_pv_done:
	s_nop 7
	v_cvt_pk_bf16_f32 v22, v240, v240
	v_cvt_pk_bf16_f32 v23, v241, v241
	v_cvt_pk_bf16_f32 v24, v242, v242
	v_cvt_pk_bf16_f32 v25, v243, v243
	v_cvt_pk_bf16_f32 v26, v244, v244
	v_cvt_pk_bf16_f32 v27, v245, v245
	v_cvt_pk_bf16_f32 v28, v246, v246
	v_cvt_pk_bf16_f32 v29, v247, v247
	v_cvt_pk_bf16_f32 v134, v248, v248
	v_cvt_pk_bf16_f32 v135, v249, v249
	v_cvt_pk_bf16_f32 v136, v250, v250
	v_cvt_pk_bf16_f32 v137, v251, v251
	v_cvt_pk_bf16_f32 v138, v120, v120
	v_cvt_pk_bf16_f32 v139, v121, v121
	v_cvt_pk_bf16_f32 v150, v122, v122
	v_cvt_pk_bf16_f32 v151, v123, v123
	global_store_short v17, v22, s[20:21]
	global_store_short v17, v23, s[20:21] offset:2048
	global_store_short v18, v24, s[20:21]
	global_store_short v18, v25, s[20:21] offset:2048
	global_store_short v17, v26, s[20:21] offset:32
	global_store_short v17, v27, s[20:21] offset:2080
	global_store_short v18, v28, s[20:21] offset:32
	global_store_short v18, v29, s[20:21] offset:2080
	global_store_short v17, v134, s[20:21] offset:64
	global_store_short v17, v135, s[20:21] offset:2112
	global_store_short v18, v136, s[20:21] offset:64
	global_store_short v18, v137, s[20:21] offset:2112
	global_store_short v17, v138, s[20:21] offset:96
	global_store_short v17, v139, s[20:21] offset:2144
	global_store_short v18, v150, s[20:21] offset:96
	global_store_short v18, v151, s[20:21] offset:2144
	s_add_u32 s3, s3, s6
	s_cmp_lt_u32 s3, 0x2000
	s_cbranch_scc1 .Lat_loop
	v_and_b32_e32 v10, 15, v0
	s_add_u32 s74, s0, 0xd8
	s_addc_u32 s75, s1, 0
	v_mov_b64_e32 v[2:3], s[74:75]
	s_mov_b64 s[64:65], exec
	s_nop 0
	s_nop 0
	s_nop 0
	s_nop 0
	s_nop 0
	s_nop 0
	s_nop 0
	s_nop 0
	s_nop 0
	s_nop 0
	s_nop 0
	s_nop 0
	s_nop 0
	s_nop 0
	s_nop 0
	s_nop 0
	s_nop 0
	s_nop 0
	s_nop 0
	s_nop 0
	s_nop 0
	s_nop 0
	s_nop 0
	s_nop 0
	s_nop 0
	s_nop 0
	s_nop 0
	s_nop 0
	s_nop 0
	s_nop 0
